# local seams: L1 invalidate issued right after the arrival atomic (overlaps the wait) instead of after the release
# speedup vs baseline: 1.0062x; 1.0062x over previous
; #define LAS __attribute__((address_space(3)))
; __device__ __forceinline__ unsigned xb_ld(unsigned* p)              { return __hip_atomic_load(p, __ATOMIC_RELAXED, __HIP_MEMORY_SCOPE_AGENT); }
; __device__ __forceinline__ unsigned xb_add(unsigned* p, unsigned v) { return __hip_atomic_fetch_add(p, v, __ATOMIC_RELAXED, __HIP_MEMORY_SCOPE_AGENT); }
; __device__ __forceinline__ unsigned xb_xcc_id() { return (unsigned)__builtin_amdgcn_s_getreg((3 << 11) | 20) & 0xFu; }
; #define XB_SPIN(cond, bar) do { unsigned _sp = 0; while (cond) { __builtin_amdgcn_s_sleep(1); \
;     if ((++_sp & 255u) == 0u) { if (xb_ld(&(bar)[XB_TMO])) break; if (_sp > XB_SPIN_CAP) { atomicAdd(&(bar)[XB_TMO], 1u); break; } } } } while (0)
; __device__ __forceinline__ bool is_leader(int wave_s) { int lane; asm volatile("v_mbcnt_lo_u32_b32 %0, -1, 0\n\tv_mbcnt_hi_u32_b32 %0, -1, %0" : "=v"(lane)); return wave_s == 0 && lane == 0; }
; __device__ __forceinline__ void grid_bar(unsigned* bar, volatile LAS unsigned* st, int wave_s, unsigned G) {
;     asm volatile("s_waitcnt vmcnt(0) lgkmcnt(0)" ::: "memory");
;     __syncthreads();
;     if (is_leader(wave_s)) {
;         const unsigned x = xb_xcc_id();
;         unsigned nloc = st[0], nx = st[1];
;         if (nloc == 0u) { xcd_barrier_complete(bar, x, G, nloc, nx); st[0] = nloc; st[1] = nx; }
;         const unsigned old = xb_add(&bar[XB_XSUB(x)], 1u);
;         const unsigned gen = old / nloc;
;         if (old + 1u == (gen + 1u) * nloc) {
;             __builtin_amdgcn_fence(__ATOMIC_RELEASE, "agent");
;             asm volatile("s_waitcnt vmcnt(0)" ::: "memory");
;             const unsigned og = xb_add(&bar[XB_TOP], 1u);
;             const unsigned tg = og / nx;
;             if (og + 1u == (tg + 1u) * nx) xb_add(&bar[XB_TOPGEN], 1u);
;             else XB_SPIN(xb_ld(&bar[XB_TOPGEN]) == tg, bar);
;             __builtin_amdgcn_fence(__ATOMIC_ACQUIRE, "agent");
;             xb_add(&bar[XB_XGEN(x)], 1u);
;             asm volatile("s_waitcnt vmcnt(0)" ::: "memory");
;         } else {
;             XB_SPIN(xb_ld(&bar[XB_XGEN(x)]) == gen, bar);
;             __builtin_amdgcn_fence(__ATOMIC_ACQUIRE, "agent");
;             asm volatile("s_waitcnt vmcnt(0)" ::: "memory");
;         }
;     }
;     __syncthreads();
; }
.LBB0_272:
	s_mov_b32 s4, s95
	s_mov_b32 s2, s94
	s_cmp_lt_i32 s2, 2
	s_cselect_b64 s[2:3], -1, 0
	s_cmp_gt_i32 s4, 1
	s_cselect_b64 s[4:5], -1, 0
	s_and_b64 s[2:3], s[2:3], s[4:5]
	s_andn2_b64 vcc, exec, s[2:3]
	s_cbranch_vccnz .LBB0_327
	s_mov_b32 s2, s94
	s_mov_b32 s4, s95
	s_cmp_lt_i32 s2, 3
	s_cselect_b64 s[2:3], -1, 0
	s_cmp_gt_i32 s4, 2
	s_cselect_b64 s[4:5], -1, 0
	s_and_b64 s[2:3], s[2:3], s[4:5]
	s_andn2_b64 vcc, exec, s[2:3]
	s_cbranch_vccnz .LBB0_327
	s_cmp_lt_u32 s79, 64
	s_waitcnt vmcnt(0) lgkmcnt(0)
	s_cselect_b64 s[2:3], -1, 0
	s_waitcnt vmcnt(0) lgkmcnt(0)
	s_barrier
	v_mbcnt_lo_u32_b32 v0, -1, 0
	v_mbcnt_hi_u32_b32 v0, -1, v0
	s_nop 0
	v_cmp_eq_u32_e32 vcc, 0, v0
	s_and_b64 s[4:5], s[2:3], vcc
	s_and_saveexec_b64 s[2:3], s[4:5]
	s_cbranch_execz .LBB0_326
	s_cmp_eq_u32 s98, 0
	s_cbranch_scc1 .Lgl_1
	s_load_dwordx2 s[4:5], s[0:1], 0xf0
	s_and_b32 s6, s78, 7
	s_lshl_b32 s6, s6, 8
	s_lshr_b32 s7, s92, 3
	s_mul_i32 s7, s7, 1
	v_mov_b32_e32 v0, s6
	v_mov_b32_e32 v1, 1
	s_waitcnt lgkmcnt(0)
	global_atomic_add v2, v0, v1, s[4:5] offset:1152 sc0
	buffer_inv sc1
	s_waitcnt vmcnt(0)
	v_readfirstlane_b32 s8, v2
	s_add_i32 s8, s8, 1
	s_cmp_eq_u32 s8, s7
	s_cbranch_scc0 .Lwt_1
	global_atomic_add v0, v1, s[4:5] offset:1216
	s_branch .Lac_1

; #define LAS __attribute__((address_space(3)))
; __device__ __forceinline__ unsigned xb_ld(unsigned* p)              { return __hip_atomic_load(p, __ATOMIC_RELAXED, __HIP_MEMORY_SCOPE_AGENT); }
; __device__ __forceinline__ unsigned xb_add(unsigned* p, unsigned v) { return __hip_atomic_fetch_add(p, v, __ATOMIC_RELAXED, __HIP_MEMORY_SCOPE_AGENT); }
; __device__ __forceinline__ unsigned xb_xcc_id() { return (unsigned)__builtin_amdgcn_s_getreg((3 << 11) | 20) & 0xFu; }
; #define XB_SPIN(cond, bar) do { unsigned _sp = 0; while (cond) { __builtin_amdgcn_s_sleep(1); \
;     if ((++_sp & 255u) == 0u) { if (xb_ld(&(bar)[XB_TMO])) break; if (_sp > XB_SPIN_CAP) { atomicAdd(&(bar)[XB_TMO], 1u); break; } } } } while (0)
; __device__ __forceinline__ bool is_leader(int wave_s) { int lane; asm volatile("v_mbcnt_lo_u32_b32 %0, -1, 0\n\tv_mbcnt_hi_u32_b32 %0, -1, %0" : "=v"(lane)); return wave_s == 0 && lane == 0; }
; __device__ __forceinline__ void grid_bar(unsigned* bar, volatile LAS unsigned* st, int wave_s, unsigned G) {
;     asm volatile("s_waitcnt vmcnt(0) lgkmcnt(0)" ::: "memory");
;     __syncthreads();
;     if (is_leader(wave_s)) {
;         const unsigned x = xb_xcc_id();
;         unsigned nloc = st[0], nx = st[1];
;         if (nloc == 0u) { xcd_barrier_complete(bar, x, G, nloc, nx); st[0] = nloc; st[1] = nx; }
;         const unsigned old = xb_add(&bar[XB_XSUB(x)], 1u);
;         const unsigned gen = old / nloc;
;         if (old + 1u == (gen + 1u) * nloc) {
;             __builtin_amdgcn_fence(__ATOMIC_RELEASE, "agent");
;             asm volatile("s_waitcnt vmcnt(0)" ::: "memory");
;             const unsigned og = xb_add(&bar[XB_TOP], 1u);
;             const unsigned tg = og / nx;
;             if (og + 1u == (tg + 1u) * nx) xb_add(&bar[XB_TOPGEN], 1u);
;             else XB_SPIN(xb_ld(&bar[XB_TOPGEN]) == tg, bar);
;             __builtin_amdgcn_fence(__ATOMIC_ACQUIRE, "agent");
;             xb_add(&bar[XB_XGEN(x)], 1u);
;             asm volatile("s_waitcnt vmcnt(0)" ::: "memory");
;         } else {
;             XB_SPIN(xb_ld(&bar[XB_XGEN(x)]) == gen, bar);
;             __builtin_amdgcn_fence(__ATOMIC_ACQUIRE, "agent");
;             asm volatile("s_waitcnt vmcnt(0)" ::: "memory");
;         }
;     }
;     __syncthreads();
; }
.Lac_1:
	s_waitcnt vmcnt(0)
	s_branch .LBB0_326

; #define LAS __attribute__((address_space(3)))
; __device__ __forceinline__ unsigned xb_ld(unsigned* p)              { return __hip_atomic_load(p, __ATOMIC_RELAXED, __HIP_MEMORY_SCOPE_AGENT); }
; __device__ __forceinline__ unsigned xb_add(unsigned* p, unsigned v) { return __hip_atomic_fetch_add(p, v, __ATOMIC_RELAXED, __HIP_MEMORY_SCOPE_AGENT); }
; __device__ __forceinline__ unsigned xb_xcc_id() { return (unsigned)__builtin_amdgcn_s_getreg((3 << 11) | 20) & 0xFu; }
; #define XB_SPIN(cond, bar) do { unsigned _sp = 0; while (cond) { __builtin_amdgcn_s_sleep(1); \
;     if ((++_sp & 255u) == 0u) { if (xb_ld(&(bar)[XB_TMO])) break; if (_sp > XB_SPIN_CAP) { atomicAdd(&(bar)[XB_TMO], 1u); break; } } } } while (0)
; __device__ __forceinline__ bool is_leader(int wave_s) { int lane; asm volatile("v_mbcnt_lo_u32_b32 %0, -1, 0\n\tv_mbcnt_hi_u32_b32 %0, -1, %0" : "=v"(lane)); return wave_s == 0 && lane == 0; }
; __device__ __forceinline__ void grid_bar(unsigned* bar, volatile LAS unsigned* st, int wave_s, unsigned G) {
;     asm volatile("s_waitcnt vmcnt(0) lgkmcnt(0)" ::: "memory");
;     __syncthreads();
;     if (is_leader(wave_s)) {
;         const unsigned x = xb_xcc_id();
;         unsigned nloc = st[0], nx = st[1];
;         if (nloc == 0u) { xcd_barrier_complete(bar, x, G, nloc, nx); st[0] = nloc; st[1] = nx; }
;         const unsigned old = xb_add(&bar[XB_XSUB(x)], 1u);
;         const unsigned gen = old / nloc;
;         if (old + 1u == (gen + 1u) * nloc) {
;             __builtin_amdgcn_fence(__ATOMIC_RELEASE, "agent");
;             asm volatile("s_waitcnt vmcnt(0)" ::: "memory");
;             const unsigned og = xb_add(&bar[XB_TOP], 1u);
;             const unsigned tg = og / nx;
;             if (og + 1u == (tg + 1u) * nx) xb_add(&bar[XB_TOPGEN], 1u);
;             else XB_SPIN(xb_ld(&bar[XB_TOPGEN]) == tg, bar);
;             __builtin_amdgcn_fence(__ATOMIC_ACQUIRE, "agent");
;             xb_add(&bar[XB_XGEN(x)], 1u);
;             asm volatile("s_waitcnt vmcnt(0)" ::: "memory");
;         } else {
;             XB_SPIN(xb_ld(&bar[XB_XGEN(x)]) == gen, bar);
;             __builtin_amdgcn_fence(__ATOMIC_ACQUIRE, "agent");
;             asm volatile("s_waitcnt vmcnt(0)" ::: "memory");
;         }
;     }
;     __syncthreads();
; }
.LBB0_826:
	s_mov_b32 s2, s94
	s_mov_b32 s4, s95
	s_cmp_lt_i32 s2, 8
	s_cselect_b64 s[2:3], -1, 0
	s_cmp_gt_i32 s4, 7
	s_cselect_b64 s[4:5], -1, 0
	s_and_b64 s[2:3], s[2:3], s[4:5]
	s_andn2_b64 vcc, exec, s[2:3]
	s_cbranch_vccnz .LBB0_881
	s_mov_b32 s2, s94
	s_mov_b32 s4, s95
	s_cmp_lt_i32 s2, 9
	s_cselect_b64 s[2:3], -1, 0
	s_cmp_gt_i32 s4, 8
	s_cselect_b64 s[4:5], -1, 0
	s_and_b64 s[2:3], s[2:3], s[4:5]
	s_andn2_b64 vcc, exec, s[2:3]
	s_cbranch_vccnz .LBB0_881
	s_cmp_lt_u32 s79, 64
	s_waitcnt vmcnt(0) lgkmcnt(0)
	s_cselect_b64 s[2:3], -1, 0
	s_waitcnt vmcnt(0) lgkmcnt(0)
	s_barrier
	v_mbcnt_lo_u32_b32 v0, -1, 0
	v_mbcnt_hi_u32_b32 v0, -1, v0
	s_nop 0
	v_cmp_eq_u32_e32 vcc, 0, v0
	s_and_b64 s[4:5], s[2:3], vcc
	s_and_saveexec_b64 s[2:3], s[4:5]
	s_cbranch_execz .LBB0_880
	s_cmp_eq_u32 s98, 0
	s_cbranch_scc1 .Lgl_2
	s_load_dwordx2 s[4:5], s[0:1], 0xf0
	s_and_b32 s6, s78, 7
	s_lshl_b32 s6, s6, 8
	s_lshr_b32 s7, s92, 3
	s_mul_i32 s7, s7, 2
	v_mov_b32_e32 v0, s6
	v_mov_b32_e32 v1, 1
	s_waitcnt lgkmcnt(0)
	global_atomic_add v2, v0, v1, s[4:5] offset:1152 sc0
	buffer_inv sc1
	s_waitcnt vmcnt(0)
	v_readfirstlane_b32 s8, v2
	s_add_i32 s8, s8, 1
	s_cmp_eq_u32 s8, s7
	s_cbranch_scc0 .Lwt_2
	global_atomic_add v0, v1, s[4:5] offset:1216
	s_branch .Lac_2

; #define LAS __attribute__((address_space(3)))
; __device__ __forceinline__ unsigned xb_ld(unsigned* p)              { return __hip_atomic_load(p, __ATOMIC_RELAXED, __HIP_MEMORY_SCOPE_AGENT); }
; __device__ __forceinline__ unsigned xb_add(unsigned* p, unsigned v) { return __hip_atomic_fetch_add(p, v, __ATOMIC_RELAXED, __HIP_MEMORY_SCOPE_AGENT); }
; __device__ __forceinline__ unsigned xb_xcc_id() { return (unsigned)__builtin_amdgcn_s_getreg((3 << 11) | 20) & 0xFu; }
; #define XB_SPIN(cond, bar) do { unsigned _sp = 0; while (cond) { __builtin_amdgcn_s_sleep(1); \
;     if ((++_sp & 255u) == 0u) { if (xb_ld(&(bar)[XB_TMO])) break; if (_sp > XB_SPIN_CAP) { atomicAdd(&(bar)[XB_TMO], 1u); break; } } } } while (0)
; __device__ __forceinline__ bool is_leader(int wave_s) { int lane; asm volatile("v_mbcnt_lo_u32_b32 %0, -1, 0\n\tv_mbcnt_hi_u32_b32 %0, -1, %0" : "=v"(lane)); return wave_s == 0 && lane == 0; }
; __device__ __forceinline__ void grid_bar(unsigned* bar, volatile LAS unsigned* st, int wave_s, unsigned G) {
;     asm volatile("s_waitcnt vmcnt(0) lgkmcnt(0)" ::: "memory");
;     __syncthreads();
;     if (is_leader(wave_s)) {
;         const unsigned x = xb_xcc_id();
;         unsigned nloc = st[0], nx = st[1];
;         if (nloc == 0u) { xcd_barrier_complete(bar, x, G, nloc, nx); st[0] = nloc; st[1] = nx; }
;         const unsigned old = xb_add(&bar[XB_XSUB(x)], 1u);
;         const unsigned gen = old / nloc;
;         if (old + 1u == (gen + 1u) * nloc) {
;             __builtin_amdgcn_fence(__ATOMIC_RELEASE, "agent");
;             asm volatile("s_waitcnt vmcnt(0)" ::: "memory");
;             const unsigned og = xb_add(&bar[XB_TOP], 1u);
;             const unsigned tg = og / nx;
;             if (og + 1u == (tg + 1u) * nx) xb_add(&bar[XB_TOPGEN], 1u);
;             else XB_SPIN(xb_ld(&bar[XB_TOPGEN]) == tg, bar);
;             __builtin_amdgcn_fence(__ATOMIC_ACQUIRE, "agent");
;             xb_add(&bar[XB_XGEN(x)], 1u);
;             asm volatile("s_waitcnt vmcnt(0)" ::: "memory");
;         } else {
;             XB_SPIN(xb_ld(&bar[XB_XGEN(x)]) == gen, bar);
;             __builtin_amdgcn_fence(__ATOMIC_ACQUIRE, "agent");
;             asm volatile("s_waitcnt vmcnt(0)" ::: "memory");
;         }
;     }
;     __syncthreads();
; }
.LBB0_956:
	s_mov_b32 s2, s94
	s_mov_b32 s4, s95
	s_cmp_lt_i32 s2, 9
	s_cselect_b64 s[2:3], -1, 0
	s_cmp_gt_i32 s4, 8
	s_cselect_b64 s[4:5], -1, 0
	s_and_b64 s[2:3], s[2:3], s[4:5]
	s_andn2_b64 vcc, exec, s[2:3]
	s_cbranch_vccnz .LBB0_1011
	s_mov_b32 s2, s94
	s_mov_b32 s4, s95
	s_cmp_lt_i32 s2, 10
	s_cselect_b64 s[2:3], -1, 0
	s_cmp_gt_i32 s4, 9
	s_cselect_b64 s[4:5], -1, 0
	s_and_b64 s[2:3], s[2:3], s[4:5]
	s_andn2_b64 vcc, exec, s[2:3]
	s_cbranch_vccnz .LBB0_1011
	s_cmp_lt_u32 s79, 64
	s_waitcnt vmcnt(0) lgkmcnt(0)
	s_cselect_b64 s[2:3], -1, 0
	s_waitcnt vmcnt(0) lgkmcnt(0)
	s_barrier
	v_mbcnt_lo_u32_b32 v0, -1, 0
	v_mbcnt_hi_u32_b32 v0, -1, v0
	s_nop 0
	v_cmp_eq_u32_e32 vcc, 0, v0
	s_and_b64 s[4:5], s[2:3], vcc
	s_and_saveexec_b64 s[2:3], s[4:5]
	s_cbranch_execz .LBB0_1010
	s_cmp_eq_u32 s98, 0
	s_cbranch_scc1 .Lgl_3
	s_load_dwordx2 s[4:5], s[0:1], 0xf0
	s_and_b32 s6, s78, 7
	s_lshl_b32 s6, s6, 8
	s_lshr_b32 s7, s92, 3
	s_mul_i32 s7, s7, 3
	v_mov_b32_e32 v0, s6
	v_mov_b32_e32 v1, 1
	s_waitcnt lgkmcnt(0)
	global_atomic_add v2, v0, v1, s[4:5] offset:1152 sc0
	buffer_inv sc1
	s_waitcnt vmcnt(0)
	v_readfirstlane_b32 s8, v2
	s_add_i32 s8, s8, 1
	s_cmp_eq_u32 s8, s7
	s_cbranch_scc0 .Lwt_3
	global_atomic_add v0, v1, s[4:5] offset:1216
	s_branch .Lac_3

; #define LAS __attribute__((address_space(3)))
; __device__ __forceinline__ unsigned xb_ld(unsigned* p)              { return __hip_atomic_load(p, __ATOMIC_RELAXED, __HIP_MEMORY_SCOPE_AGENT); }
; __device__ __forceinline__ unsigned xb_add(unsigned* p, unsigned v) { return __hip_atomic_fetch_add(p, v, __ATOMIC_RELAXED, __HIP_MEMORY_SCOPE_AGENT); }
; __device__ __forceinline__ unsigned xb_xcc_id() { return (unsigned)__builtin_amdgcn_s_getreg((3 << 11) | 20) & 0xFu; }
; #define XB_SPIN(cond, bar) do { unsigned _sp = 0; while (cond) { __builtin_amdgcn_s_sleep(1); \
;     if ((++_sp & 255u) == 0u) { if (xb_ld(&(bar)[XB_TMO])) break; if (_sp > XB_SPIN_CAP) { atomicAdd(&(bar)[XB_TMO], 1u); break; } } } } while (0)
; __device__ __forceinline__ bool is_leader(int wave_s) { int lane; asm volatile("v_mbcnt_lo_u32_b32 %0, -1, 0\n\tv_mbcnt_hi_u32_b32 %0, -1, %0" : "=v"(lane)); return wave_s == 0 && lane == 0; }
; __device__ __forceinline__ void grid_bar(unsigned* bar, volatile LAS unsigned* st, int wave_s, unsigned G) {
;     asm volatile("s_waitcnt vmcnt(0) lgkmcnt(0)" ::: "memory");
;     __syncthreads();
;     if (is_leader(wave_s)) {
;         const unsigned x = xb_xcc_id();
;         unsigned nloc = st[0], nx = st[1];
;         if (nloc == 0u) { xcd_barrier_complete(bar, x, G, nloc, nx); st[0] = nloc; st[1] = nx; }
;         const unsigned old = xb_add(&bar[XB_XSUB(x)], 1u);
;         const unsigned gen = old / nloc;
;         if (old + 1u == (gen + 1u) * nloc) {
;             __builtin_amdgcn_fence(__ATOMIC_RELEASE, "agent");
;             asm volatile("s_waitcnt vmcnt(0)" ::: "memory");
;             const unsigned og = xb_add(&bar[XB_TOP], 1u);
;             const unsigned tg = og / nx;
;             if (og + 1u == (tg + 1u) * nx) xb_add(&bar[XB_TOPGEN], 1u);
;             else XB_SPIN(xb_ld(&bar[XB_TOPGEN]) == tg, bar);
;             __builtin_amdgcn_fence(__ATOMIC_ACQUIRE, "agent");
;             xb_add(&bar[XB_XGEN(x)], 1u);
;             asm volatile("s_waitcnt vmcnt(0)" ::: "memory");
;         } else {
;             XB_SPIN(xb_ld(&bar[XB_XGEN(x)]) == gen, bar);
;             __builtin_amdgcn_fence(__ATOMIC_ACQUIRE, "agent");
;             asm volatile("s_waitcnt vmcnt(0)" ::: "memory");
;         }
;     }
;     __syncthreads();
; }
.LBB0_1057:
	s_mov_b32 s2, s94
	s_mov_b32 s4, s95
	s_cmp_lt_i32 s2, 10
	s_cselect_b64 s[2:3], -1, 0
	s_cmp_gt_i32 s4, 9
	s_cselect_b64 s[4:5], -1, 0
	s_and_b64 s[2:3], s[2:3], s[4:5]
	s_andn2_b64 vcc, exec, s[2:3]
	s_cbranch_vccnz .LBB0_1112
	s_mov_b32 s2, s94
	s_mov_b32 s4, s95
	s_cmp_lt_i32 s2, 11
	s_cselect_b64 s[2:3], -1, 0
	s_cmp_gt_i32 s4, 10
	s_cselect_b64 s[4:5], -1, 0
	s_and_b64 s[2:3], s[2:3], s[4:5]
	s_andn2_b64 vcc, exec, s[2:3]
	s_cbranch_vccnz .LBB0_1112
	s_cmp_lt_u32 s79, 64
	s_waitcnt vmcnt(0) lgkmcnt(0)
	s_cselect_b64 s[2:3], -1, 0
	s_waitcnt vmcnt(0) lgkmcnt(0)
	s_barrier
	v_mbcnt_lo_u32_b32 v0, -1, 0
	v_mbcnt_hi_u32_b32 v0, -1, v0
	s_nop 0
	v_cmp_eq_u32_e32 vcc, 0, v0
	s_and_b64 s[4:5], s[2:3], vcc
	s_and_saveexec_b64 s[2:3], s[4:5]
	s_cbranch_execz .LBB0_1111
	s_cmp_eq_u32 s98, 0
	s_cbranch_scc1 .Lgl_4
	s_load_dwordx2 s[4:5], s[0:1], 0xf0
	s_and_b32 s6, s78, 7
	s_lshl_b32 s6, s6, 8
	s_lshr_b32 s7, s92, 3
	s_mul_i32 s7, s7, 4
	v_mov_b32_e32 v0, s6
	v_mov_b32_e32 v1, 1
	s_waitcnt lgkmcnt(0)
	global_atomic_add v2, v0, v1, s[4:5] offset:1152 sc0
	buffer_inv sc1
	s_waitcnt vmcnt(0)
	v_readfirstlane_b32 s8, v2
	s_add_i32 s8, s8, 1
	s_cmp_eq_u32 s8, s7
	s_cbranch_scc0 .Lwt_4
	global_atomic_add v0, v1, s[4:5] offset:1216
	s_branch .Lac_4

; #define LAS __attribute__((address_space(3)))
; __device__ __forceinline__ unsigned xb_ld(unsigned* p)              { return __hip_atomic_load(p, __ATOMIC_RELAXED, __HIP_MEMORY_SCOPE_AGENT); }
; __device__ __forceinline__ unsigned xb_add(unsigned* p, unsigned v) { return __hip_atomic_fetch_add(p, v, __ATOMIC_RELAXED, __HIP_MEMORY_SCOPE_AGENT); }
; __device__ __forceinline__ unsigned xb_xcc_id() { return (unsigned)__builtin_amdgcn_s_getreg((3 << 11) | 20) & 0xFu; }
; #define XB_SPIN(cond, bar) do { unsigned _sp = 0; while (cond) { __builtin_amdgcn_s_sleep(1); \
;     if ((++_sp & 255u) == 0u) { if (xb_ld(&(bar)[XB_TMO])) break; if (_sp > XB_SPIN_CAP) { atomicAdd(&(bar)[XB_TMO], 1u); break; } } } } while (0)
; __device__ __forceinline__ bool is_leader(int wave_s) { int lane; asm volatile("v_mbcnt_lo_u32_b32 %0, -1, 0\n\tv_mbcnt_hi_u32_b32 %0, -1, %0" : "=v"(lane)); return wave_s == 0 && lane == 0; }
; __device__ __forceinline__ void grid_bar(unsigned* bar, volatile LAS unsigned* st, int wave_s, unsigned G) {
;     asm volatile("s_waitcnt vmcnt(0) lgkmcnt(0)" ::: "memory");
;     __syncthreads();
;     if (is_leader(wave_s)) {
;         const unsigned x = xb_xcc_id();
;         unsigned nloc = st[0], nx = st[1];
;         if (nloc == 0u) { xcd_barrier_complete(bar, x, G, nloc, nx); st[0] = nloc; st[1] = nx; }
;         const unsigned old = xb_add(&bar[XB_XSUB(x)], 1u);
;         const unsigned gen = old / nloc;
;         if (old + 1u == (gen + 1u) * nloc) {
;             __builtin_amdgcn_fence(__ATOMIC_RELEASE, "agent");
;             asm volatile("s_waitcnt vmcnt(0)" ::: "memory");
;             const unsigned og = xb_add(&bar[XB_TOP], 1u);
;             const unsigned tg = og / nx;
;             if (og + 1u == (tg + 1u) * nx) xb_add(&bar[XB_TOPGEN], 1u);
;             else XB_SPIN(xb_ld(&bar[XB_TOPGEN]) == tg, bar);
;             __builtin_amdgcn_fence(__ATOMIC_ACQUIRE, "agent");
;             xb_add(&bar[XB_XGEN(x)], 1u);
;             asm volatile("s_waitcnt vmcnt(0)" ::: "memory");
;         } else {
;             XB_SPIN(xb_ld(&bar[XB_XGEN(x)]) == gen, bar);
;             __builtin_amdgcn_fence(__ATOMIC_ACQUIRE, "agent");
;             asm volatile("s_waitcnt vmcnt(0)" ::: "memory");
;         }
;     }
;     __syncthreads();
; }
.LBB0_1132:
	s_mov_b32 s4, s95
	s_mov_b32 s2, s94
	s_cmp_lt_i32 s2, 11
	s_cselect_b64 s[2:3], -1, 0
	s_cmp_gt_i32 s4, 10
	s_cselect_b64 s[4:5], -1, 0
	s_and_b64 s[2:3], s[2:3], s[4:5]
	s_andn2_b64 vcc, exec, s[2:3]
	s_cbranch_vccnz .LBB0_1187
	s_mov_b32 s4, s95
	s_mov_b32 s2, s94
	s_cmp_lt_i32 s2, 12
	s_cselect_b64 s[2:3], -1, 0
	s_cmp_gt_i32 s4, 11
	s_cselect_b64 s[4:5], -1, 0
	s_and_b64 s[2:3], s[2:3], s[4:5]
	s_andn2_b64 vcc, exec, s[2:3]
	s_cbranch_vccnz .LBB0_1187
	s_cmp_lt_u32 s79, 64
	s_waitcnt vmcnt(0) lgkmcnt(0)
	s_cselect_b64 s[2:3], -1, 0
	s_waitcnt vmcnt(0) lgkmcnt(0)
	s_barrier
	v_mbcnt_lo_u32_b32 v0, -1, 0
	v_mbcnt_hi_u32_b32 v0, -1, v0
	s_nop 0
	v_cmp_eq_u32_e32 vcc, 0, v0
	s_and_b64 s[4:5], s[2:3], vcc
	s_and_saveexec_b64 s[2:3], s[4:5]
	s_cbranch_execz .LBB0_1186
	s_cmp_eq_u32 s98, 0
	s_cbranch_scc1 .Lgl_5
	s_load_dwordx2 s[4:5], s[0:1], 0xf0
	s_and_b32 s6, s78, 7
	s_lshl_b32 s6, s6, 8
	s_lshr_b32 s7, s92, 3
	s_mul_i32 s7, s7, 5
	v_mov_b32_e32 v0, s6
	v_mov_b32_e32 v1, 1
	s_waitcnt lgkmcnt(0)
	global_atomic_add v2, v0, v1, s[4:5] offset:1152 sc0
	buffer_inv sc1
	s_waitcnt vmcnt(0)
	v_readfirstlane_b32 s8, v2
	s_add_i32 s8, s8, 1
	s_cmp_eq_u32 s8, s7
	s_cbranch_scc0 .Lwt_5
	global_atomic_add v0, v1, s[4:5] offset:1216
	s_branch .Lac_5

; #define LAS __attribute__((address_space(3)))
; __device__ __forceinline__ unsigned xb_ld(unsigned* p)              { return __hip_atomic_load(p, __ATOMIC_RELAXED, __HIP_MEMORY_SCOPE_AGENT); }
; __device__ __forceinline__ unsigned xb_add(unsigned* p, unsigned v) { return __hip_atomic_fetch_add(p, v, __ATOMIC_RELAXED, __HIP_MEMORY_SCOPE_AGENT); }
; __device__ __forceinline__ unsigned xb_xcc_id() { return (unsigned)__builtin_amdgcn_s_getreg((3 << 11) | 20) & 0xFu; }
; #define XB_SPIN(cond, bar) do { unsigned _sp = 0; while (cond) { __builtin_amdgcn_s_sleep(1); \
;     if ((++_sp & 255u) == 0u) { if (xb_ld(&(bar)[XB_TMO])) break; if (_sp > XB_SPIN_CAP) { atomicAdd(&(bar)[XB_TMO], 1u); break; } } } } while (0)
; __device__ __forceinline__ bool is_leader(int wave_s) { int lane; asm volatile("v_mbcnt_lo_u32_b32 %0, -1, 0\n\tv_mbcnt_hi_u32_b32 %0, -1, %0" : "=v"(lane)); return wave_s == 0 && lane == 0; }
; __device__ __forceinline__ void grid_bar(unsigned* bar, volatile LAS unsigned* st, int wave_s, unsigned G) {
;     asm volatile("s_waitcnt vmcnt(0) lgkmcnt(0)" ::: "memory");
;     __syncthreads();
;     if (is_leader(wave_s)) {
;         const unsigned x = xb_xcc_id();
;         unsigned nloc = st[0], nx = st[1];
;         if (nloc == 0u) { xcd_barrier_complete(bar, x, G, nloc, nx); st[0] = nloc; st[1] = nx; }
;         const unsigned old = xb_add(&bar[XB_XSUB(x)], 1u);
;         const unsigned gen = old / nloc;
;         if (old + 1u == (gen + 1u) * nloc) {
;             __builtin_amdgcn_fence(__ATOMIC_RELEASE, "agent");
;             asm volatile("s_waitcnt vmcnt(0)" ::: "memory");
;             const unsigned og = xb_add(&bar[XB_TOP], 1u);
;             const unsigned tg = og / nx;
;             if (og + 1u == (tg + 1u) * nx) xb_add(&bar[XB_TOPGEN], 1u);
;             else XB_SPIN(xb_ld(&bar[XB_TOPGEN]) == tg, bar);
;             __builtin_amdgcn_fence(__ATOMIC_ACQUIRE, "agent");
;             xb_add(&bar[XB_XGEN(x)], 1u);
;             asm volatile("s_waitcnt vmcnt(0)" ::: "memory");
;         } else {
;             XB_SPIN(xb_ld(&bar[XB_XGEN(x)]) == gen, bar);
;             __builtin_amdgcn_fence(__ATOMIC_ACQUIRE, "agent");
;             asm volatile("s_waitcnt vmcnt(0)" ::: "memory");
;         }
;     }
;     __syncthreads();
; }
.LBB0_1236:
	s_mov_b32 s2, s94
	s_mov_b32 s4, s95
	s_cmp_lt_i32 s2, 12
	s_cselect_b64 s[2:3], -1, 0
	s_cmp_gt_i32 s4, 11
	s_cselect_b64 s[4:5], -1, 0
	s_and_b64 s[2:3], s[2:3], s[4:5]
	s_andn2_b64 vcc, exec, s[2:3]
	s_cbranch_vccnz .LBB0_1291
	s_mov_b32 s2, s94
	s_mov_b32 s4, s95
	s_cmp_lt_i32 s2, 13
	s_cselect_b64 s[2:3], -1, 0
	s_cmp_gt_i32 s4, 12
	s_cselect_b64 s[4:5], -1, 0
	s_and_b64 s[2:3], s[2:3], s[4:5]
	s_andn2_b64 vcc, exec, s[2:3]
	s_cbranch_vccnz .LBB0_1291
	s_cmp_lt_u32 s79, 64
	s_waitcnt vmcnt(0) lgkmcnt(0)
	s_cselect_b64 s[2:3], -1, 0
	s_waitcnt vmcnt(0) lgkmcnt(0)
	s_barrier
	v_mbcnt_lo_u32_b32 v0, -1, 0
	v_mbcnt_hi_u32_b32 v0, -1, v0
	s_nop 0
	v_cmp_eq_u32_e32 vcc, 0, v0
	s_and_b64 s[4:5], s[2:3], vcc
	s_and_saveexec_b64 s[2:3], s[4:5]
	s_cbranch_execz .LBB0_1290
	s_cmp_eq_u32 s98, 0
	s_cbranch_scc1 .Lgl_6
	s_load_dwordx2 s[4:5], s[0:1], 0xf0
	s_and_b32 s6, s78, 7
	s_lshl_b32 s6, s6, 8
	s_lshr_b32 s7, s92, 3
	s_mul_i32 s7, s7, 6
	v_mov_b32_e32 v0, s6
	v_mov_b32_e32 v1, 1
	s_waitcnt lgkmcnt(0)
	global_atomic_add v2, v0, v1, s[4:5] offset:1152 sc0
	buffer_inv sc1
	s_waitcnt vmcnt(0)
	v_readfirstlane_b32 s8, v2
	s_add_i32 s8, s8, 1
	s_cmp_eq_u32 s8, s7
	s_cbranch_scc0 .Lwt_6
	global_atomic_add v0, v1, s[4:5] offset:1216
	s_branch .Lac_6

; #define LAS __attribute__((address_space(3)))
; __device__ __forceinline__ unsigned xb_ld(unsigned* p)              { return __hip_atomic_load(p, __ATOMIC_RELAXED, __HIP_MEMORY_SCOPE_AGENT); }
; __device__ __forceinline__ unsigned xb_add(unsigned* p, unsigned v) { return __hip_atomic_fetch_add(p, v, __ATOMIC_RELAXED, __HIP_MEMORY_SCOPE_AGENT); }
; __device__ __forceinline__ unsigned xb_xcc_id() { return (unsigned)__builtin_amdgcn_s_getreg((3 << 11) | 20) & 0xFu; }
; #define XB_SPIN(cond, bar) do { unsigned _sp = 0; while (cond) { __builtin_amdgcn_s_sleep(1); \
;     if ((++_sp & 255u) == 0u) { if (xb_ld(&(bar)[XB_TMO])) break; if (_sp > XB_SPIN_CAP) { atomicAdd(&(bar)[XB_TMO], 1u); break; } } } } while (0)
; __device__ __forceinline__ bool is_leader(int wave_s) { int lane; asm volatile("v_mbcnt_lo_u32_b32 %0, -1, 0\n\tv_mbcnt_hi_u32_b32 %0, -1, %0" : "=v"(lane)); return wave_s == 0 && lane == 0; }
; __device__ __forceinline__ void grid_bar(unsigned* bar, volatile LAS unsigned* st, int wave_s, unsigned G) {
;     asm volatile("s_waitcnt vmcnt(0) lgkmcnt(0)" ::: "memory");
;     __syncthreads();
;     if (is_leader(wave_s)) {
;         const unsigned x = xb_xcc_id();
;         unsigned nloc = st[0], nx = st[1];
;         if (nloc == 0u) { xcd_barrier_complete(bar, x, G, nloc, nx); st[0] = nloc; st[1] = nx; }
;         const unsigned old = xb_add(&bar[XB_XSUB(x)], 1u);
;         const unsigned gen = old / nloc;
;         if (old + 1u == (gen + 1u) * nloc) {
;             __builtin_amdgcn_fence(__ATOMIC_RELEASE, "agent");
;             asm volatile("s_waitcnt vmcnt(0)" ::: "memory");
;             const unsigned og = xb_add(&bar[XB_TOP], 1u);
;             const unsigned tg = og / nx;
;             if (og + 1u == (tg + 1u) * nx) xb_add(&bar[XB_TOPGEN], 1u);
;             else XB_SPIN(xb_ld(&bar[XB_TOPGEN]) == tg, bar);
;             __builtin_amdgcn_fence(__ATOMIC_ACQUIRE, "agent");
;             xb_add(&bar[XB_XGEN(x)], 1u);
;             asm volatile("s_waitcnt vmcnt(0)" ::: "memory");
;         } else {
;             XB_SPIN(xb_ld(&bar[XB_XGEN(x)]) == gen, bar);
;             __builtin_amdgcn_fence(__ATOMIC_ACQUIRE, "agent");
;             asm volatile("s_waitcnt vmcnt(0)" ::: "memory");
;         }
;     }
;     __syncthreads();
; }
.LBB0_1532:
	s_mov_b32 s2, s94
	s_mov_b32 s4, s95
	s_cmp_lt_i32 s2, 15
	s_cselect_b64 s[2:3], -1, 0
	s_cmp_gt_i32 s4, 14
	s_cselect_b64 s[4:5], -1, 0
	s_and_b64 s[2:3], s[2:3], s[4:5]
	s_andn2_b64 vcc, exec, s[2:3]
	s_cbranch_vccnz .LBB0_1587
	s_mov_b32 s2, s94
	s_mov_b32 s4, s95
	s_cmp_lt_i32 s2, 16
	s_cselect_b64 s[2:3], -1, 0
	s_cmp_gt_i32 s4, 15
	s_cselect_b64 s[4:5], -1, 0
	s_and_b64 s[2:3], s[2:3], s[4:5]
	s_andn2_b64 vcc, exec, s[2:3]
	s_cbranch_vccnz .LBB0_1587
	s_cmp_lt_u32 s79, 64
	s_waitcnt vmcnt(0) lgkmcnt(0)
	s_cselect_b64 s[2:3], -1, 0
	s_waitcnt vmcnt(0) lgkmcnt(0)
	s_barrier
	v_mbcnt_lo_u32_b32 v0, -1, 0
	v_mbcnt_hi_u32_b32 v0, -1, v0
	s_nop 0
	v_cmp_eq_u32_e32 vcc, 0, v0
	s_and_b64 s[4:5], s[2:3], vcc
	s_and_saveexec_b64 s[2:3], s[4:5]
	s_cbranch_execz .LBB0_1586
	s_cmp_eq_u32 s98, 0
	s_cbranch_scc1 .Lgl_7
	s_load_dwordx2 s[4:5], s[0:1], 0xf0
	s_and_b32 s6, s78, 7
	s_lshl_b32 s6, s6, 8
	s_lshr_b32 s7, s92, 3
	s_mul_i32 s7, s7, 7
	v_mov_b32_e32 v0, s6
	v_mov_b32_e32 v1, 1
	s_waitcnt lgkmcnt(0)
	global_atomic_add v2, v0, v1, s[4:5] offset:1152 sc0
	buffer_inv sc1
	s_waitcnt vmcnt(0)
	v_readfirstlane_b32 s8, v2
	s_add_i32 s8, s8, 1
	s_cmp_eq_u32 s8, s7
	s_cbranch_scc0 .Lwt_7
	global_atomic_add v0, v1, s[4:5] offset:1216
	s_branch .Lac_7

; #define LAS __attribute__((address_space(3)))
; __device__ __forceinline__ unsigned xb_ld(unsigned* p)              { return __hip_atomic_load(p, __ATOMIC_RELAXED, __HIP_MEMORY_SCOPE_AGENT); }
; __device__ __forceinline__ unsigned xb_add(unsigned* p, unsigned v) { return __hip_atomic_fetch_add(p, v, __ATOMIC_RELAXED, __HIP_MEMORY_SCOPE_AGENT); }
; __device__ __forceinline__ unsigned xb_xcc_id() { return (unsigned)__builtin_amdgcn_s_getreg((3 << 11) | 20) & 0xFu; }
; #define XB_SPIN(cond, bar) do { unsigned _sp = 0; while (cond) { __builtin_amdgcn_s_sleep(1); \
;     if ((++_sp & 255u) == 0u) { if (xb_ld(&(bar)[XB_TMO])) break; if (_sp > XB_SPIN_CAP) { atomicAdd(&(bar)[XB_TMO], 1u); break; } } } } while (0)
; __device__ __forceinline__ bool is_leader(int wave_s) { int lane; asm volatile("v_mbcnt_lo_u32_b32 %0, -1, 0\n\tv_mbcnt_hi_u32_b32 %0, -1, %0" : "=v"(lane)); return wave_s == 0 && lane == 0; }
; __device__ __forceinline__ void grid_bar(unsigned* bar, volatile LAS unsigned* st, int wave_s, unsigned G) {
;     asm volatile("s_waitcnt vmcnt(0) lgkmcnt(0)" ::: "memory");
;     __syncthreads();
;     if (is_leader(wave_s)) {
;         const unsigned x = xb_xcc_id();
;         unsigned nloc = st[0], nx = st[1];
;         if (nloc == 0u) { xcd_barrier_complete(bar, x, G, nloc, nx); st[0] = nloc; st[1] = nx; }
;         const unsigned old = xb_add(&bar[XB_XSUB(x)], 1u);
;         const unsigned gen = old / nloc;
;         if (old + 1u == (gen + 1u) * nloc) {
;             __builtin_amdgcn_fence(__ATOMIC_RELEASE, "agent");
;             asm volatile("s_waitcnt vmcnt(0)" ::: "memory");
;             const unsigned og = xb_add(&bar[XB_TOP], 1u);
;             const unsigned tg = og / nx;
;             if (og + 1u == (tg + 1u) * nx) xb_add(&bar[XB_TOPGEN], 1u);
;             else XB_SPIN(xb_ld(&bar[XB_TOPGEN]) == tg, bar);
;             __builtin_amdgcn_fence(__ATOMIC_ACQUIRE, "agent");
;             xb_add(&bar[XB_XGEN(x)], 1u);
;             asm volatile("s_waitcnt vmcnt(0)" ::: "memory");
;         } else {
;             XB_SPIN(xb_ld(&bar[XB_XGEN(x)]) == gen, bar);
;             __builtin_amdgcn_fence(__ATOMIC_ACQUIRE, "agent");
;             asm volatile("s_waitcnt vmcnt(0)" ::: "memory");
;         }
;     }
;     __syncthreads();
; }
.LBB0_1658:
	s_mov_b32 s2, s94
	s_mov_b32 s4, s95
	s_cmp_lt_i32 s2, 17
	s_cselect_b64 s[2:3], -1, 0
	s_cmp_gt_i32 s4, 16
	s_cselect_b64 s[4:5], -1, 0
	s_and_b64 s[2:3], s[2:3], s[4:5]
	s_andn2_b64 vcc, exec, s[2:3]
	s_cbranch_vccnz .LBB0_1713
	s_mov_b32 s2, s94
	s_mov_b32 s4, s95
	s_cmp_lt_i32 s2, 18
	s_cselect_b64 s[2:3], -1, 0
	s_cmp_gt_i32 s4, 17
	s_cselect_b64 s[4:5], -1, 0
	s_and_b64 s[2:3], s[2:3], s[4:5]
	s_andn2_b64 vcc, exec, s[2:3]
	s_cbranch_vccnz .LBB0_1713
	s_cmp_lt_u32 s79, 64
	s_waitcnt vmcnt(0) lgkmcnt(0)
	s_cselect_b64 s[2:3], -1, 0
	s_waitcnt vmcnt(0) lgkmcnt(0)
	s_barrier
	v_mbcnt_lo_u32_b32 v0, -1, 0
	v_mbcnt_hi_u32_b32 v0, -1, v0
	s_nop 0
	v_cmp_eq_u32_e32 vcc, 0, v0
	s_and_b64 s[4:5], s[2:3], vcc
	s_and_saveexec_b64 s[2:3], s[4:5]
	s_cbranch_execz .LBB0_1712
	s_cmp_eq_u32 s98, 0
	s_cbranch_scc1 .Lgl_8
	s_load_dwordx2 s[4:5], s[0:1], 0xf0
	s_and_b32 s6, s78, 7
	s_lshl_b32 s6, s6, 8
	s_lshr_b32 s7, s92, 3
	s_mul_i32 s7, s7, 8
	v_mov_b32_e32 v0, s6
	v_mov_b32_e32 v1, 1
	s_waitcnt lgkmcnt(0)
	global_atomic_add v2, v0, v1, s[4:5] offset:1152 sc0
	buffer_inv sc1
	s_waitcnt vmcnt(0)
	v_readfirstlane_b32 s8, v2
	s_add_i32 s8, s8, 1
	s_cmp_eq_u32 s8, s7
	s_cbranch_scc0 .Lwt_8
	global_atomic_add v0, v1, s[4:5] offset:1216
	s_branch .Lac_8

; #define LAS __attribute__((address_space(3)))
; __device__ __forceinline__ unsigned xb_ld(unsigned* p)              { return __hip_atomic_load(p, __ATOMIC_RELAXED, __HIP_MEMORY_SCOPE_AGENT); }
; __device__ __forceinline__ unsigned xb_add(unsigned* p, unsigned v) { return __hip_atomic_fetch_add(p, v, __ATOMIC_RELAXED, __HIP_MEMORY_SCOPE_AGENT); }
; __device__ __forceinline__ unsigned xb_xcc_id() { return (unsigned)__builtin_amdgcn_s_getreg((3 << 11) | 20) & 0xFu; }
; #define XB_SPIN(cond, bar) do { unsigned _sp = 0; while (cond) { __builtin_amdgcn_s_sleep(1); \
;     if ((++_sp & 255u) == 0u) { if (xb_ld(&(bar)[XB_TMO])) break; if (_sp > XB_SPIN_CAP) { atomicAdd(&(bar)[XB_TMO], 1u); break; } } } } while (0)
; __device__ __forceinline__ bool is_leader(int wave_s) { int lane; asm volatile("v_mbcnt_lo_u32_b32 %0, -1, 0\n\tv_mbcnt_hi_u32_b32 %0, -1, %0" : "=v"(lane)); return wave_s == 0 && lane == 0; }
; __device__ __forceinline__ void grid_bar(unsigned* bar, volatile LAS unsigned* st, int wave_s, unsigned G) {
;     asm volatile("s_waitcnt vmcnt(0) lgkmcnt(0)" ::: "memory");
;     __syncthreads();
;     if (is_leader(wave_s)) {
;         const unsigned x = xb_xcc_id();
;         unsigned nloc = st[0], nx = st[1];
;         if (nloc == 0u) { xcd_barrier_complete(bar, x, G, nloc, nx); st[0] = nloc; st[1] = nx; }
;         const unsigned old = xb_add(&bar[XB_XSUB(x)], 1u);
;         const unsigned gen = old / nloc;
;         if (old + 1u == (gen + 1u) * nloc) {
;             __builtin_amdgcn_fence(__ATOMIC_RELEASE, "agent");
;             asm volatile("s_waitcnt vmcnt(0)" ::: "memory");
;             const unsigned og = xb_add(&bar[XB_TOP], 1u);
;             const unsigned tg = og / nx;
;             if (og + 1u == (tg + 1u) * nx) xb_add(&bar[XB_TOPGEN], 1u);
;             else XB_SPIN(xb_ld(&bar[XB_TOPGEN]) == tg, bar);
;             __builtin_amdgcn_fence(__ATOMIC_ACQUIRE, "agent");
;             xb_add(&bar[XB_XGEN(x)], 1u);
;             asm volatile("s_waitcnt vmcnt(0)" ::: "memory");
;         } else {
;             XB_SPIN(xb_ld(&bar[XB_XGEN(x)]) == gen, bar);
;             __builtin_amdgcn_fence(__ATOMIC_ACQUIRE, "agent");
;             asm volatile("s_waitcnt vmcnt(0)" ::: "memory");
;         }
;     }
;     __syncthreads();
; }
.LBB0_1832:
	s_mov_b32 s2, s94
	s_mov_b32 s4, s95
	s_cmp_lt_i32 s2, 19
	s_cselect_b64 s[2:3], -1, 0
	s_cmp_gt_i32 s4, 18
	s_cselect_b64 s[4:5], -1, 0
	s_and_b64 s[2:3], s[2:3], s[4:5]
	s_andn2_b64 vcc, exec, s[2:3]
	s_cbranch_vccnz .LBB0_1887
	s_mov_b32 s2, s94
	s_mov_b32 s4, s95
	s_cmp_lt_i32 s2, 20
	s_cselect_b64 s[2:3], -1, 0
	s_cmp_gt_i32 s4, 19
	s_cselect_b64 s[4:5], -1, 0
	s_and_b64 s[2:3], s[2:3], s[4:5]
	s_andn2_b64 vcc, exec, s[2:3]
	s_cbranch_vccnz .LBB0_1887
	s_cmp_lt_u32 s79, 64
	s_waitcnt vmcnt(0) lgkmcnt(0)
	s_cselect_b64 s[2:3], -1, 0
	s_waitcnt vmcnt(0) lgkmcnt(0)
	s_barrier
	v_mbcnt_lo_u32_b32 v0, -1, 0
	v_mbcnt_hi_u32_b32 v0, -1, v0
	s_nop 0
	v_cmp_eq_u32_e32 vcc, 0, v0
	s_and_b64 s[4:5], s[2:3], vcc
	s_and_saveexec_b64 s[2:3], s[4:5]
	s_cbranch_execz .LBB0_1886
	s_cmp_eq_u32 s98, 0
	s_cbranch_scc1 .Lgl_9
	s_load_dwordx2 s[4:5], s[0:1], 0xf0
	s_and_b32 s6, s78, 7
	s_lshl_b32 s6, s6, 8
	s_lshr_b32 s7, s92, 3
	s_mul_i32 s7, s7, 9
	v_mov_b32_e32 v0, s6
	v_mov_b32_e32 v1, 1
	s_waitcnt lgkmcnt(0)
	global_atomic_add v2, v0, v1, s[4:5] offset:1152 sc0
	buffer_inv sc1
	s_waitcnt vmcnt(0)
	v_readfirstlane_b32 s8, v2
	s_add_i32 s8, s8, 1
	s_cmp_eq_u32 s8, s7
	s_cbranch_scc0 .Lwt_9
	global_atomic_add v0, v1, s[4:5] offset:1216
	s_branch .Lac_9

; #define LAS __attribute__((address_space(3)))
; __device__ __forceinline__ unsigned xb_ld(unsigned* p)              { return __hip_atomic_load(p, __ATOMIC_RELAXED, __HIP_MEMORY_SCOPE_AGENT); }
; __device__ __forceinline__ unsigned xb_add(unsigned* p, unsigned v) { return __hip_atomic_fetch_add(p, v, __ATOMIC_RELAXED, __HIP_MEMORY_SCOPE_AGENT); }
; __device__ __forceinline__ unsigned xb_xcc_id() { return (unsigned)__builtin_amdgcn_s_getreg((3 << 11) | 20) & 0xFu; }
; #define XB_SPIN(cond, bar) do { unsigned _sp = 0; while (cond) { __builtin_amdgcn_s_sleep(1); \
;     if ((++_sp & 255u) == 0u) { if (xb_ld(&(bar)[XB_TMO])) break; if (_sp > XB_SPIN_CAP) { atomicAdd(&(bar)[XB_TMO], 1u); break; } } } } while (0)
; __device__ __forceinline__ bool is_leader(int wave_s) { int lane; asm volatile("v_mbcnt_lo_u32_b32 %0, -1, 0\n\tv_mbcnt_hi_u32_b32 %0, -1, %0" : "=v"(lane)); return wave_s == 0 && lane == 0; }
; __device__ __forceinline__ void grid_bar(unsigned* bar, volatile LAS unsigned* st, int wave_s, unsigned G) {
;     asm volatile("s_waitcnt vmcnt(0) lgkmcnt(0)" ::: "memory");
;     __syncthreads();
;     if (is_leader(wave_s)) {
;         const unsigned x = xb_xcc_id();
;         unsigned nloc = st[0], nx = st[1];
;         if (nloc == 0u) { xcd_barrier_complete(bar, x, G, nloc, nx); st[0] = nloc; st[1] = nx; }
;         const unsigned old = xb_add(&bar[XB_XSUB(x)], 1u);
;         const unsigned gen = old / nloc;
;         if (old + 1u == (gen + 1u) * nloc) {
;             __builtin_amdgcn_fence(__ATOMIC_RELEASE, "agent");
;             asm volatile("s_waitcnt vmcnt(0)" ::: "memory");
;             const unsigned og = xb_add(&bar[XB_TOP], 1u);
;             const unsigned tg = og / nx;
;             if (og + 1u == (tg + 1u) * nx) xb_add(&bar[XB_TOPGEN], 1u);
;             else XB_SPIN(xb_ld(&bar[XB_TOPGEN]) == tg, bar);
;             __builtin_amdgcn_fence(__ATOMIC_ACQUIRE, "agent");
;             xb_add(&bar[XB_XGEN(x)], 1u);
;             asm volatile("s_waitcnt vmcnt(0)" ::: "memory");
;         } else {
;             XB_SPIN(xb_ld(&bar[XB_XGEN(x)]) == gen, bar);
;             __builtin_amdgcn_fence(__ATOMIC_ACQUIRE, "agent");
;             asm volatile("s_waitcnt vmcnt(0)" ::: "memory");
;         }
;     }
;     __syncthreads();
; }
.LBB0_1962:
	s_mov_b32 s2, s94
	s_mov_b32 s4, s95
	s_cmp_lt_i32 s2, 20
	s_cselect_b64 s[2:3], -1, 0
	s_cmp_gt_i32 s4, 19
	s_cselect_b64 s[4:5], -1, 0
	s_and_b64 s[2:3], s[2:3], s[4:5]
	s_andn2_b64 vcc, exec, s[2:3]
	s_cbranch_vccnz .LBB0_2017
	s_mov_b32 s2, s94
	s_mov_b32 s4, s95
	s_cmp_lt_i32 s2, 21
	s_cselect_b64 s[2:3], -1, 0
	s_cmp_gt_i32 s4, 20
	s_cselect_b64 s[4:5], -1, 0
	s_and_b64 s[2:3], s[2:3], s[4:5]
	s_andn2_b64 vcc, exec, s[2:3]
	s_cbranch_vccnz .LBB0_2017
	s_cmp_lt_u32 s79, 64
	s_waitcnt vmcnt(0) lgkmcnt(0)
	s_cselect_b64 s[2:3], -1, 0
	s_waitcnt vmcnt(0) lgkmcnt(0)
	s_barrier
	v_mbcnt_lo_u32_b32 v0, -1, 0
	v_mbcnt_hi_u32_b32 v0, -1, v0
	s_nop 0
	v_cmp_eq_u32_e32 vcc, 0, v0
	s_and_b64 s[4:5], s[2:3], vcc
	s_and_saveexec_b64 s[2:3], s[4:5]
	s_cbranch_execz .LBB0_2016
	s_cmp_eq_u32 s98, 0
	s_cbranch_scc1 .Lgl_10
	s_load_dwordx2 s[4:5], s[0:1], 0xf0
	s_and_b32 s6, s78, 7
	s_lshl_b32 s6, s6, 8
	s_lshr_b32 s7, s92, 3
	s_mul_i32 s7, s7, 10
	v_mov_b32_e32 v0, s6
	v_mov_b32_e32 v1, 1
	s_waitcnt lgkmcnt(0)
	global_atomic_add v2, v0, v1, s[4:5] offset:1152 sc0
	buffer_inv sc1
	s_waitcnt vmcnt(0)
	v_readfirstlane_b32 s8, v2
	s_add_i32 s8, s8, 1
	s_cmp_eq_u32 s8, s7
	s_cbranch_scc0 .Lwt_10
	global_atomic_add v0, v1, s[4:5] offset:1216
	s_branch .Lac_10
